# group barriers (4-CU same-XCD) at P3-P4, P4-P5 (+P3-done split-phase counter), P5-P6
# speedup vs baseline: 1.0267x; 1.0267x over previous
; #define LAS __attribute__((address_space(3)))
; __device__ __forceinline__ XcdBarrier xcd_barrier_post(unsigned* bar, volatile LAS unsigned* st) {
;     XcdBarrier b; b.bar = bar; b.x = xb_xcc_id(); b.st = st;
;     if (threadIdx.x == 0) (void)xb_add(&bar[XB_XCNT(b.x)], 1u);
;     return b;
; }
; __global__ void __launch_bounds__(NWAVES * 64, 2) mk_fwd(Args a) {
;     ...
;     const int tid = threadIdx.x, lane = tid & 63, wave = __builtin_amdgcn_readfirstlane(tid >> 6);
;     const int G = gridDim.x, bx = blockIdx.x;
;     const int vcu = (G % 8 == 0) ? (bx % 8) * (G / 8) + bx / 8 : bx;
;     unsigned char* ws = a.ws;
;     const float* x_in = (const float*)a.in[0]; const int* positions = (const int*)a.in[1];
;     const float* mix_norm = (const float*)a.in[2]; const float* w_in = (const float*)a.in[3];
;     const float* lq1 = (const float*)a.in[4]; const float* lk1 = (const float*)a.in[5]; const float* lq2 = (const float*)a.in[6]; const float* lk2 = (const float*)a.in[7];
;     const float* subln_w = (const float*)a.in[8]; const float* conv_w = (const float*)a.in[9];
;     const float* w_a = (const float*)a.in[10]; const float* w_b = (const float*)a.in[11]; const float* w_o = (const float*)a.in[12];
;     const float* ffn_norm = (const float*)a.in[13]; const float* w_gate = (const float*)a.in[14]; const float* w_up = (const float*)a.in[15]; const float* w_down = (const float*)a.in[16];
;     const float* final_norm = (const float*)a.in[17];
;     float* out = a.out;
;     float* rope = (float*)(ws + WS_ROPE); float* ssqA = (float*)(ws + WS_SSQA); float* ssqB = (float*)(ws + WS_SSQB); float* lamtab = (float*)(ws + WS_LAM);
;     bf16u* XB = (bf16u*)(ws + WS_XB);
;     bf16u* Qb = (bf16u*)(ws + WS_Q); bf16u* Kb = Qb + BUFE; bf16u* Vb = Qb + 2 * BUFE; bf16u* BGb = Qb + 3 * BUFE; bf16u* CGb = Qb + 4 * BUFE; bf16u* Ub = Qb + 5 * BUFE;
;     bf16u* SGA = Qb + 6 * BUFE; bf16u* SGB = Qb + 7 * BUFE;
;     bf16u* ACT = (bf16u*)(ws + WS_ACT); float* STASH = (float*)(ws + WS_STASH);
;     bf16u* O1 = (bf16u*)(ws + WS_O1); bf16u* O2 = (bf16u*)(ws + WS_O2); bf16u* MIXED = O1;
;     const int gw = vcu * NWAVES + wave, NGW = G * NWAVES;
;     volatile LAS unsigned* MISC = (volatile LAS unsigned*)(L + LDS_BYTES - 64);
;     if (tid < 2) MISC[tid] = 0u;
;     __syncthreads();
;     const XcdBarrier bar = xcd_barrier_post((unsigned*)(ws + WS_BAR), MISC);
.LBB0_3:
	v_writelane_b32 v253, s6, 1
	s_or_b64 exec, exec, s[2:3]
	s_load_dwordx16 s[36:51], s[0:1], 0x0
	s_waitcnt lgkmcnt(0)
	s_barrier
	s_add_u32 s2, s18, 0x310000
	v_writelane_b32 v253, s36, 2
	s_getreg_b32 s4, hwreg(HW_REG_XCC_ID, 0, 4)
	s_addc_u32 s3, s19, 0
	v_writelane_b32 v253, s37, 3
	v_writelane_b32 v253, s38, 4
	v_writelane_b32 v253, s39, 5
	v_writelane_b32 v253, s40, 6
	v_writelane_b32 v253, s41, 7
	v_writelane_b32 v253, s42, 8
	v_writelane_b32 v253, s43, 9
	v_writelane_b32 v253, s44, 10
	v_writelane_b32 v253, s45, 11
	v_writelane_b32 v253, s46, 12
	v_writelane_b32 v253, s47, 13
	v_writelane_b32 v253, s48, 14
	v_writelane_b32 v253, s49, 15
	v_writelane_b32 v253, s50, 16
	v_writelane_b32 v253, s51, 17
	v_writelane_b32 v253, s0, 18
	s_load_dwordx16 s[36:51], s[0:1], 0x40
	s_and_b32 s20, s4, 15
	v_writelane_b32 v253, s1, 19
	v_cmp_eq_u32_e64 s[0:1], 0, v244
	s_waitcnt lgkmcnt(0)
	v_writelane_b32 v253, s36, 20
	s_nop 1
	v_writelane_b32 v253, s37, 21
	v_writelane_b32 v253, s38, 22
	v_writelane_b32 v253, s39, 23
	v_writelane_b32 v253, s40, 24
	v_writelane_b32 v253, s41, 25
	v_writelane_b32 v253, s42, 26
	v_writelane_b32 v253, s43, 27
	v_writelane_b32 v253, s44, 28
	v_writelane_b32 v253, s45, 29
	v_writelane_b32 v253, s46, 30
	v_writelane_b32 v253, s47, 31
	v_writelane_b32 v253, s48, 32
	v_writelane_b32 v253, s49, 33
	v_writelane_b32 v253, s50, 34
	v_writelane_b32 v253, s51, 35
	v_writelane_b32 v253, s0, 36
	s_nop 1
	v_writelane_b32 v253, s1, 37
	s_and_saveexec_b64 s[4:5], s[0:1]
	s_cbranch_execz .LBB0_6
	s_mov_b64 s[6:7], exec
	v_mbcnt_lo_u32_b32 v1, s6, 0
	v_mbcnt_hi_u32_b32 v1, s7, v1
	v_cmp_eq_u32_e32 vcc, 0, v1
	s_and_b64 s[8:9], exec, vcc
	s_mov_b64 exec, s[8:9]
	s_cbranch_execz .LBB0_6
	s_lshl_b32 s8, s20, 8
	s_bcnt1_i32_b64 s6, s[6:7]
	v_mov_b32_e32 v1, s8
	v_mov_b32_e32 v2, s6
	global_atomic_add v1, v2, s[2:3] offset:1024
	v_readlane_b32 s8, v253, 1
	s_nop 3
	s_lshl_b32 s8, s8, 2
	s_add_i32 s8, s8, 0x8000
	s_add_i32 s9, s20, 1
	v_mov_b32_e32 v1, s8
	v_mov_b32_e32 v2, s9
	global_atomic_add v1, v2, s[2:3]

; #define LAS __attribute__((address_space(3)))
; __global__ void __launch_bounds__(NWAVES * 64, 2) mk_fwd(Args a) {
;     ...
;     float* rope = (float*)(ws + WS_ROPE); float* ssqA = (float*)(ws + WS_SSQA); float* ssqB = (float*)(ws + WS_SSQB); float* lamtab = (float*)(ws + WS_LAM);
;     bf16u* XB = (bf16u*)(ws + WS_XB);
;     bf16u* Qb = (bf16u*)(ws + WS_Q); bf16u* Kb = Qb + BUFE; bf16u* Vb = Qb + 2 * BUFE; bf16u* BGb = Qb + 3 * BUFE; bf16u* CGb = Qb + 4 * BUFE; bf16u* Ub = Qb + 5 * BUFE;
;     bf16u* SGA = Qb + 6 * BUFE; bf16u* SGB = Qb + 7 * BUFE;
;     bf16u* ACT = (bf16u*)(ws + WS_ACT); float* STASH = (float*)(ws + WS_STASH);
;     bf16u* O1 = (bf16u*)(ws + WS_O1); bf16u* O2 = (bf16u*)(ws + WS_O2); bf16u* MIXED = O1;
;     const int gw = vcu * NWAVES + wave, NGW = G * NWAVES;
;     volatile LAS unsigned* MISC = (volatile LAS unsigned*)(L + LDS_BYTES - 64);
;     if (tid < 2) MISC[tid] = 0u;
;     __syncthreads();
;     const XcdBarrier bar = xcd_barrier_post((unsigned*)(ws + WS_BAR), MISC);
; #pragma unroll 1
;     for (int rep0 = 0; rep0 < REP_P0; ++rep0) {
;         CONVERT_LAYER(0, gw, NGW, lane);
;         for (int idx = (vcu * NWAVES * 64) + tid; idx < NTOK * 8; idx += G * NWAVES * 64) {
;             const int row = idx >> 3, j = idx & 7;
;             const float ang = (float)positions[row] * a.freq[j];
;             rope[(size_t)row * 16 + j] = cosf(ang); rope[(size_t)row * 16 + 8 + j] = sinf(ang);
;         }
;         for (int m = gw; m < NTOK; m += NGW) {
;             const f32x4* xr = (const f32x4*)(x_in + (size_t)m * DMOD) + lane;
;             f32x4 v[4]; float s = 0.f;
; #pragma unroll
;             for (int j = 0; j < 4; ++j) { v[j] = xr[64 * j]; s += (v[j].x * v[j].x + v[j].y * v[j].y) + (v[j].z * v[j].z + v[j].w * v[j].w); }
;             s = wave_sum(s);
;             unsigned long long* o8 = (unsigned long long*)(XB + (size_t)m * DMOD) + lane;
; #pragma unroll
;             for (int j = 0; j < 4; ++j) o8[64 * j] = (unsigned long long)pk2(v[j].x, v[j].y) | ((unsigned long long)pk2(v[j].z, v[j].w) << 32);
;             if (lane < 16) ssqA[(size_t)m * 16 + lane] = (lane == 0) ? s : 0.f;
;         }
;         if (vcu == 0 && wave == 0) {
;             for (int l = 0; l < NLAYER; ++l) {
;                 const float s1 = wave_sum(lq1[l * 64 + lane] * lk1[l * 64 + lane]), s2 = wave_sum(lq2[l * 64 + lane] * lk2[l * 64 + lane]);
.LBB0_135:
	v_writelane_b32 v255, s72, 2
	s_nop 1
	v_writelane_b32 v255, s73, 3
	s_or_b64 exec, exec, s[2:3]
	s_add_u32 s0, s42, 0x100000
	s_addc_u32 s1, s43, 0
	v_writelane_b32 v255, s0, 4
	v_readlane_b32 s4, v253, 38
	s_mov_b32 s91, 0
	v_writelane_b32 v255, s1, 5
	s_add_u32 s0, s42, 0x200000
	s_addc_u32 s1, s43, 0
	s_add_u32 s82, s42, 0x9e00000
	s_addc_u32 s83, s43, 0
	s_add_u32 s6, s42, 0xbe00000
	v_writelane_b32 v255, s0, 6
	s_addc_u32 s7, s43, 0
	v_mov_b32_e32 v245, 0x358637bd
	v_writelane_b32 v255, s1, 7
	s_add_u32 s0, s42, 0xde00000
	v_writelane_b32 v255, s0, 8
	s_addc_u32 s0, s43, 0
	v_writelane_b32 v255, s0, 9
	s_add_u32 s0, s42, 0xfe00000
	v_writelane_b32 v255, s0, 10
	s_addc_u32 s0, s43, 0
	s_add_u32 s28, s42, 0x11e00000
	s_addc_u32 s29, s43, 0
	s_add_u32 s30, s42, 0x13e00000
	s_addc_u32 s31, s43, 0
	v_writelane_b32 v255, s0, 11
	s_add_u32 s0, s42, 0x17e00000
	s_addc_u32 s1, s43, 0
	v_writelane_b32 v255, s0, 12
	s_movk_i32 s61, 0x2000
	v_mov_b32_e32 v1, 0
	v_writelane_b32 v255, s1, 13
	s_add_u32 s0, s42, 0x19e00000
	s_addc_u32 s1, s43, 0
	s_add_u32 s14, s42, 0x1be00000
	s_addc_u32 s15, s43, 0
	s_add_u32 s86, s42, 0x1de00000
	s_addc_u32 s87, s43, 0
	s_ashr_i32 s79, s80, 31
	v_writelane_b32 v255, s0, 14
	s_cmpk_eq_i32 s80, 0x100
	s_mov_b32 s88, 0x8000
	v_writelane_b32 v255, s1, 15
	s_cselect_b64 s[0:1], -1, 0
	v_writelane_b32 v255, s0, 16
	s_lshl_b32 s89, s80, 2
	s_mov_b32 s27, 0xa000
	v_writelane_b32 v255, s1, 17
	s_abs_i32 s0, s80
	s_waitcnt lgkmcnt(0)
	v_cvt_f32_u32_e32 v0, s0
	s_lshl_b32 s1, s4, 5
	v_writelane_b32 v255, s1, 18
	s_sub_i32 s1, 0, s0
	v_rcp_iflag_f32_e32 v0, v0
	s_mov_b32 s26, 0xc000
	v_mov_b32_e32 v234, 1
	s_movk_i32 s10, 0x3ff
	v_mul_f32_e32 v0, 0x4f7ffffe, v0
	v_cvt_u32_f32_e32 v0, v0
	v_mov_b64_e32 v[236:237], 0x800
	v_mov_b32_e32 v235, 0x3e38aa3b
	v_mov_b32_e32 v248, 0xff800000
	v_readfirstlane_b32 s2, v0
	s_mul_i32 s1, s1, s2
	s_mul_hi_u32 s1, s2, s1
	s_add_i32 s2, s2, s1
	s_mul_hi_u32 s1, s2, 0x580
	s_mul_i32 s1, s1, s0
	s_sub_i32 s1, 0x580, s1
	s_sub_i32 s2, s1, s0
	s_cmp_ge_u32 s1, s0
	s_cselect_b32 s1, s2, s1
	s_sub_i32 s2, s1, s0
	s_cmp_ge_u32 s1, s0
	s_cselect_b32 s5, s2, s1
	s_cmp_eq_u32 s5, 0
	s_cselect_b64 s[2:3], -1, 0
	s_sub_i32 s0, s80, s5
	s_lshl_b32 s0, s0, 3
	v_writelane_b32 v255, s0, 19
	s_lshl_b32 s0, s80, 4
	v_writelane_b32 v255, s0, 20
	s_lshl_b32 s0, s4, 6
	s_lshl_b32 s1, s5, 9
	s_sub_i32 s8, s0, s1
	s_sub_i32 s0, s34, s1
	v_writelane_b32 v255, s0, 21
	s_lshl_b32 s0, s4, 2
	s_lshl_b32 s1, s5, 5
	s_sub_i32 s0, s0, s1
	v_writelane_b32 v255, s0, 22
	s_lshl_b32 s0, s80, 5
	s_sub_i32 s0, s0, s1
	v_writelane_b32 v255, s0, 23
	s_lshl_b32 s0, s4, 7
	s_lshl_b32 s1, s5, 10
	s_sub_i32 s0, s0, s1
	s_add_i32 s0, s0, 0xfff92000
	v_writelane_b32 v255, s0, 24
	s_lshl_b32 s0, s80, 10
	s_sub_i32 s0, s0, s1
	v_writelane_b32 v255, s0, 25
	s_lshl_b32 s0, s5, 3
	s_sub_i32 s1, s4, s0
	s_add_i32 s4, s1, 0xfffff240
	v_writelane_b32 v255, s4, 26
	s_mov_b32 s4, s74
	v_writelane_b32 v255, s4, 27
	s_sub_i32 s0, s74, s0
	s_xor_b64 s[2:3], s[2:3], -1
	v_writelane_b32 v255, s5, 28
	v_writelane_b32 v255, s0, 29
	s_add_i32 s0, s8, 0xfffc9000
	v_writelane_b32 v255, s0, 30
	s_add_i32 s0, s1, 0xfffff500
	v_writelane_b32 v255, s0, 31
	s_add_i32 s0, s1, 0xf500
	v_writelane_b32 v255, s0, 32
	v_writelane_b32 v255, s8, 33
	s_add_i32 s0, s8, 0xfffd4000
	v_writelane_b32 v255, s0, 34
	s_lshl_b32 s0, s80, 12
	s_lshl_b32 s1, s5, 12
	v_writelane_b32 v255, s5, 35
	s_sub_i32 s0, s0, s1
	v_writelane_b32 v255, s0, 36
	s_add_i32 s1, 0, 0x23fc0
	v_writelane_b32 v255, s1, 37
	s_add_i32 s1, 0, 0x23fc4
	v_writelane_b32 v255, s1, 38
	v_writelane_b32 v255, s2, 39
	s_lshl_b32 s44, s80, 6
	s_mov_b32 s5, 0x18000
	v_writelane_b32 v255, s3, 40
	v_writelane_b32 v255, s78, 41
	v_writelane_b32 v255, s82, 42
	s_mov_b32 s0, 0x50000
	v_mov_b64_e32 v[230:231], 0xff
	v_writelane_b32 v255, s83, 43
	s_mov_b32 s11, 0x41000000
	s_mov_b64 s[8:9], 0x40000
	s_mov_b64 s[70:71], 0x80
	s_mov_b64 s[62:63], 0x2000
	s_mov_b64 s[94:95], 0x20000
	s_mov_b64 s[72:73], 0x60000
	s_mov_b64 s[74:75], 0x80000
	s_mov_b64 s[66:67], 0xfe40000
	s_mov_b64 s[84:85], 0xfe40080
	s_mov_b32 s92, s91
	v_writelane_b32 v255, s79, 44
	s_barrier
	s_mov_b32 s98, 0
	s_mov_b32 s99, 0
	s_cmpk_lg_i32 s80, 0x100
	s_cbranch_scc1 .Lgb_setup_done
	s_add_u32 s12, s42, 0x318000
	s_addc_u32 s13, s43, 0
	v_and_b32_e32 v2, 63, v244
	v_lshlrev_b32_e32 v3, 4, v2
	global_load_dwordx4 v[4:7], v3, s[12:13] sc1
	v_and_b32_e32 v8, 1, v2
	s_waitcnt vmcnt(0)
	v_readlane_b32 s1, v4, 0
	v_readlane_b32 s2, v5, 0
	v_readlane_b32 s3, v6, 0
	v_readlane_b32 s4, v7, 0
	v_readlane_b32 s16, v4, 1
	v_readlane_b32 s17, v5, 1
	v_readlane_b32 s18, v6, 1
	v_readlane_b32 s19, v7, 1
	v_cmp_eq_u32_e32 vcc, 1, v8
	s_nop 3
	v_mov_b32_e32 v9, s1
	v_mov_b32_e32 v10, s16
	v_cndmask_b32_e32 v9, v9, v10, vcc
	v_mov_b32_e32 v11, s2
	v_mov_b32_e32 v10, s17
	v_cndmask_b32_e32 v11, v11, v10, vcc
	v_mov_b32_e32 v12, s3
	v_mov_b32_e32 v10, s18
	v_cndmask_b32_e32 v12, v12, v10, vcc
	v_mov_b32_e32 v13, s4
	v_mov_b32_e32 v10, s19
	v_cndmask_b32_e32 v13, v13, v10, vcc
	v_xor_b32_e32 v9, v9, v4
	v_xor_b32_e32 v11, v11, v5
	v_xor_b32_e32 v12, v12, v6
	v_xor_b32_e32 v13, v13, v7
	v_or3_b32 v9, v9, v11, v12
	v_or_b32_e32 v9, v9, v13
	v_min_u32_e32 v10, v4, v5
	v_min3_u32 v10, v10, v6, v7
	v_cmp_ne_u32_e32 vcc, 0, v9
	v_cmp_eq_u32_e64 s[2:3], 0, v10
	s_nop 1
	s_or_b64 s[2:3], s[2:3], vcc
	s_cmp_lg_u64 s[2:3], 0
	s_cbranch_scc1 .Lgb_setup_done
	s_mov_b32 s98, 1
.Lgb_setup_done:
	s_branch .LBB0_138

; __device__ __forceinline__ unsigned xb_ld(unsigned* p)              { return __hip_atomic_load(p, __ATOMIC_RELAXED, __HIP_MEMORY_SCOPE_AGENT); }
; __device__ __forceinline__ unsigned xb_add(unsigned* p, unsigned v) { return __hip_atomic_fetch_add(p, v, __ATOMIC_RELAXED, __HIP_MEMORY_SCOPE_AGENT); }
; #define XB_SPIN(cond, bar) do { unsigned _sp = 0; while (cond) { __builtin_amdgcn_s_sleep(1); \
;     if ((++_sp & 255u) == 0u) { if (xb_ld(&(bar)[XB_TMO])) break; if (_sp > XB_SPIN_CAP) { atomicAdd(&(bar)[XB_TMO], 1u); break; } } } } while (0)
; #define GSYNC() do { for (int r_ = 0; r_ < REP_SYNC; ++r_) xcd_barrier(bar); } while (0)
; __device__ __forceinline__ void xcd_barrier(const XcdBarrier& b) {
;     asm volatile("s_waitcnt vmcnt(0)" ::: "memory");
;     __syncthreads();
;     if (threadIdx.x == 0) {
;         unsigned* bar = b.bar;
;         __builtin_amdgcn_s_waitcnt(0);
;         unsigned nloc = b.st[0], nx = b.st[1];
;         if (nloc == 0u) { xcd_barrier_complete(bar, b.x, nloc, nx); b.st[0] = nloc; b.st[1] = nx; }
;         const unsigned old = xb_add(&bar[XB_XSUB(b.x)], 1u);
;         const unsigned gen = old / nloc;
;         if (old + 1u == (gen + 1u) * nloc) {
;             __builtin_amdgcn_fence(__ATOMIC_RELEASE, "agent");
;             asm volatile("s_waitcnt vmcnt(0)" ::: "memory");
;             const unsigned og = xb_add(&bar[XB_TOP], 1u);
;             const unsigned tg = og / nx;
;             if (og + 1u == (tg + 1u) * nx) xb_add(&bar[XB_TOPGEN], 1u);
;             else XB_SPIN(xb_ld(&bar[XB_TOPGEN]) == tg, bar);
;             __builtin_amdgcn_fence(__ATOMIC_ACQUIRE, "agent");
;             xb_add(&bar[XB_XGEN(b.x)], 1u);
;             asm volatile("s_waitcnt vmcnt(0)" ::: "memory");
;         } else {
;             XB_SPIN(xb_ld(&bar[XB_XGEN(b.x)]) == gen, bar);
;             __builtin_amdgcn_fence(__ATOMIC_ACQUIRE, "agent");
;             asm volatile("s_waitcnt vmcnt(0)" ::: "memory");
;         }
;     }
;     __syncthreads();
; }
; __global__ void __launch_bounds__(NWAVES * 64, 2) mk_fwd(Args a) {
;     ...
;         GSYNC();
.LBB0_441:
	s_waitcnt vmcnt(0)
	s_barrier
	s_mov_b64 s[2:3], exec
	v_readlane_b32 s12, v253, 36
	v_readlane_b32 s13, v253, 37
	s_and_b64 s[12:13], s[2:3], s[12:13]
	s_mov_b64 exec, s[12:13]
	s_cbranch_execz .LBB0_493
	s_cmp_lg_u32 s98, 0
	s_cbranch_scc0 .Lgb_full_493
	v_readlane_b32 s4, v253, 1
	v_readlane_b32 s12, v253, 56
	v_readlane_b32 s13, v253, 57
	s_add_i32 s99, s99, 4
	s_nop 2
	s_and_b32 s4, s4, 63
	s_lshl_b32 s4, s4, 7
	s_add_i32 s4, s4, 0x3e00
	v_mov_b32_e32 v2, s4
	s_mov_b32 s1, 0
	s_nop 1
	global_atomic_add v2, v234, s[12:13]
	v_mov_b32_e32 v3, 0x5e00
	global_atomic_add v3, v234, s[12:13]
.Lgb_spin_493:
	global_load_dword v3, v2, s[12:13] sc1
	s_waitcnt vmcnt(0)
	v_readfirstlane_b32 s4, v3
	s_nop 3
	s_cmp_ge_u32 s4, s99
	s_cbranch_scc1 .Lgb_done_493
	s_sleep 1
	s_add_i32 s1, s1, 1
	s_cmp_lt_u32 s1, 0x40000
	s_cbranch_scc1 .Lgb_spin_493
.Lgb_done_493:
	buffer_inv sc1
	s_waitcnt vmcnt(0)
	s_branch .LBB0_493
.Lgb_full_493:
	v_readlane_b32 s1, v255, 37
	s_waitcnt vmcnt(0) expcnt(0) lgkmcnt(0)
	s_nop 0
	v_mov_b32_e32 v0, s1
	ds_read_b32 v3, v0
	v_readlane_b32 s1, v255, 38
	s_waitcnt lgkmcnt(0)
	v_cmp_ne_u32_e32 vcc, 0, v3
	v_mov_b32_e32 v0, s1
	ds_read_b32 v2, v0
	s_cbranch_vccnz .LBB0_457
	s_mov_b32 s1, 1
	s_branch .LBB0_445

; __device__ __forceinline__ unsigned xb_add(unsigned* p, unsigned v) { return __hip_atomic_fetch_add(p, v, __ATOMIC_RELAXED, __HIP_MEMORY_SCOPE_AGENT); }
; #define GSYNC() do { for (int r_ = 0; r_ < REP_SYNC; ++r_) xcd_barrier(bar); } while (0)
; __device__ __forceinline__ void xcd_barrier(const XcdBarrier& b) {
;     asm volatile("s_waitcnt vmcnt(0)" ::: "memory");
;     __syncthreads();
;     if (threadIdx.x == 0) {
;         unsigned* bar = b.bar;
;         __builtin_amdgcn_s_waitcnt(0);
;         unsigned nloc = b.st[0], nx = b.st[1];
;         if (nloc == 0u) { xcd_barrier_complete(bar, b.x, nloc, nx); b.st[0] = nloc; b.st[1] = nx; }
;         const unsigned old = xb_add(&bar[XB_XSUB(b.x)], 1u);
;         const unsigned gen = old / nloc;
;         if (old + 1u == (gen + 1u) * nloc) {
; __global__ void __launch_bounds__(NWAVES * 64, 2) mk_fwd(Args a) {
;     ...
;         GSYNC();
.LBB0_517:
	s_waitcnt vmcnt(0)
	s_barrier
	s_mov_b64 s[2:3], exec
	v_readlane_b32 s12, v253, 36
	v_readlane_b32 s13, v253, 37
	s_and_b64 s[12:13], s[2:3], s[12:13]
	s_mov_b64 exec, s[12:13]
	s_cbranch_execz .LBB0_569
	s_cmp_lg_u32 s98, 0
	s_cbranch_scc0 .Lgb_full_569
	v_readlane_b32 s4, v253, 1
	v_readlane_b32 s12, v253, 56
	v_readlane_b32 s13, v253, 57
	s_add_i32 s99, s99, 4
	s_nop 2
	s_and_b32 s4, s4, 63
	s_lshl_b32 s4, s4, 7
	s_add_i32 s4, s4, 0x3e00
	v_mov_b32_e32 v2, s4
	s_mov_b32 s1, 0
	s_nop 1
	global_atomic_add v2, v234, s[12:13]

; #define GSYNC() do { for (int r_ = 0; r_ < REP_SYNC; ++r_) xcd_barrier(bar); } while (0)
; __global__ void __launch_bounds__(NWAVES * 64, 2) mk_fwd(Args a) {
;     ...
;         GSYNC();
.Lgb_done_569:
	v_mov_b32_e32 v2, 0x5e00
	s_lshl_b32 s4, s92, 8
	s_add_i32 s4, s4, 0x100
	s_mov_b32 s1, 0
.Lgb_spin2_569:
	global_load_dword v3, v2, s[12:13] sc1
	s_waitcnt vmcnt(0)
	v_readfirstlane_b32 s16, v3
	s_nop 3
	s_cmp_ge_u32 s16, s4
	s_cbranch_scc1 .Lgb_done2_569
	s_sleep 1
	s_add_i32 s1, s1, 1
	s_cmp_lt_u32 s1, 0x40000
	s_cbranch_scc1 .Lgb_spin2_569

; __device__ __forceinline__ unsigned xb_add(unsigned* p, unsigned v) { return __hip_atomic_fetch_add(p, v, __ATOMIC_RELAXED, __HIP_MEMORY_SCOPE_AGENT); }
; #define GSYNC() do { for (int r_ = 0; r_ < REP_SYNC; ++r_) xcd_barrier(bar); } while (0)
; __device__ __forceinline__ void xcd_barrier(const XcdBarrier& b) {
;     asm volatile("s_waitcnt vmcnt(0)" ::: "memory");
;     __syncthreads();
;     if (threadIdx.x == 0) {
;         unsigned* bar = b.bar;
;         __builtin_amdgcn_s_waitcnt(0);
;         unsigned nloc = b.st[0], nx = b.st[1];
;         if (nloc == 0u) { xcd_barrier_complete(bar, b.x, nloc, nx); b.st[0] = nloc; b.st[1] = nx; }
;         const unsigned old = xb_add(&bar[XB_XSUB(b.x)], 1u);
;         const unsigned gen = old / nloc;
;         if (old + 1u == (gen + 1u) * nloc) {
; __global__ void __launch_bounds__(NWAVES * 64, 2) mk_fwd(Args a) {
;     ...
;         GSYNC();
.LBB0_628:
	s_waitcnt vmcnt(0)
	s_waitcnt vmcnt(0)
	s_barrier
	s_mov_b64 s[16:17], exec
	v_readlane_b32 s12, v253, 36
	v_readlane_b32 s13, v253, 37
	s_and_b64 s[12:13], s[16:17], s[12:13]
	s_mov_b64 exec, s[12:13]
	s_cbranch_execz .LBB0_680
	s_cmp_lg_u32 s98, 0
	s_cbranch_scc0 .Lgb_full_680
	v_readlane_b32 s4, v253, 1
	v_readlane_b32 s12, v253, 56
	v_readlane_b32 s13, v253, 57
	s_add_i32 s99, s99, 4
	s_nop 2
	s_and_b32 s4, s4, 63
	s_lshl_b32 s4, s4, 7
	s_add_i32 s4, s4, 0x3e00
	v_mov_b32_e32 v2, s4
	s_mov_b32 s1, 0
	s_nop 1
	global_atomic_add v2, v234, s[12:13]

; __global__ void __launch_bounds__(NWAVES * 64, 2) mk_fwd(Args a) {
	.amdhsa_kernel _Z6mk_fwd4Args
		.amdhsa_group_segment_fixed_size 0
		.amdhsa_private_segment_fixed_size 0
		.amdhsa_kernarg_size 464
		.amdhsa_user_sgpr_count 2
		.amdhsa_user_sgpr_dispatch_ptr 0
		.amdhsa_user_sgpr_queue_ptr 0
		.amdhsa_user_sgpr_kernarg_segment_ptr 1
		.amdhsa_user_sgpr_dispatch_id 0
		.amdhsa_user_sgpr_kernarg_preload_length 0
		.amdhsa_user_sgpr_kernarg_preload_offset 0
		.amdhsa_user_sgpr_private_segment_size 0
		.amdhsa_uses_dynamic_stack 0
		.amdhsa_enable_private_segment 0
		.amdhsa_system_sgpr_workgroup_id_x 1
		.amdhsa_system_sgpr_workgroup_id_y 0
		.amdhsa_system_sgpr_workgroup_id_z 0
		.amdhsa_system_sgpr_workgroup_info 0
		.amdhsa_system_vgpr_workitem_id 2
		.amdhsa_next_free_vgpr 256
		.amdhsa_next_free_sgpr 102
		.amdhsa_accum_offset 256
		.amdhsa_reserve_vcc 1
		.amdhsa_float_round_mode_32 0
		.amdhsa_float_round_mode_16_64 0
		.amdhsa_float_denorm_mode_32 3
		.amdhsa_float_denorm_mode_16_64 3
		.amdhsa_dx10_clamp 1
		.amdhsa_ieee_mode 1
		.amdhsa_fp16_overflow 0
		.amdhsa_tg_split 0
		.amdhsa_exception_fp_ieee_invalid_op 0
		.amdhsa_exception_fp_denorm_src 0
		.amdhsa_exception_fp_ieee_div_zero 0
		.amdhsa_exception_fp_ieee_overflow 0
		.amdhsa_exception_fp_ieee_underflow 0
		.amdhsa_exception_fp_ieee_inexact 0
		.amdhsa_exception_int_div_zero 0
	.end_amdhsa_kernel

; __global__ void __launch_bounds__(NWAVES * 64, 2) mk_fwd(Args a) {
amdhsa.kernels:
  - .agpr_count:     0
    .args:
      - .offset:         0
        .size:           208
        .value_kind:     by_value
      - .offset:         208
        .size:           4
        .value_kind:     hidden_block_count_x
      - .offset:         212
        .size:           4
        .value_kind:     hidden_block_count_y
      - .offset:         216
        .size:           4
        .value_kind:     hidden_block_count_z
      - .offset:         220
        .size:           2
        .value_kind:     hidden_group_size_x
      - .offset:         222
        .size:           2
        .value_kind:     hidden_group_size_y
      - .offset:         224
        .size:           2
        .value_kind:     hidden_group_size_z
      - .offset:         226
        .size:           2
        .value_kind:     hidden_remainder_x
      - .offset:         228
        .size:           2
        .value_kind:     hidden_remainder_y
      - .offset:         230
        .size:           2
        .value_kind:     hidden_remainder_z
      - .offset:         248
        .size:           8
        .value_kind:     hidden_global_offset_x
      - .offset:         256
        .size:           8
        .value_kind:     hidden_global_offset_y
      - .offset:         264
        .size:           8
        .value_kind:     hidden_global_offset_z
      - .offset:         272
        .size:           2
        .value_kind:     hidden_grid_dims
      - .offset:         296
        .size:           8
        .value_kind:     hidden_multigrid_sync_arg
      - .offset:         328
        .size:           4
        .value_kind:     hidden_dynamic_lds_size
    .group_segment_fixed_size: 0
    .kernarg_segment_align: 8
    .kernarg_segment_size: 464
    .language:       OpenCL C
    .language_version:
      - 2
      - 0
    .max_flat_workgroup_size: 512
    .name:           _Z6mk_fwd4Args
    .private_segment_fixed_size: 0
    .sgpr_count:     108
    .sgpr_spill_count: 181
    .symbol:         _Z6mk_fwd4Args.kd
    .uniform_work_group_size: 1
    .uses_dynamic_stack: false
    .vgpr_count:     256
    .vgpr_spill_count: 0
    .wavefront_size: 64
